# k23: scan loader wave forms its eleven LDS-DMA addresses with SALU on SGPR bases (saddr addressing) instead of 64-bit VALU adds
# speedup vs baseline: 1.0115x; 1.0115x over previous
.LBB0_812:
	s_and_b64 vcc, exec, s[46:47]
	s_cbranch_vccz .LBB0_841
	v_and_b32_e32 v0, 31, v128
	v_lshrrev_b32_e32 v1, 5, v148
	s_cmp_lt_u32 s61, 64
	v_mul_u32_u24_e32 v76, 0x90, v0
	v_lshlrev_b32_e32 v77, 3, v1
	v_mul_u32_u24_e32 v78, 24, v0
	v_and_b32_e32 v79, 32, v128
	v_lshlrev_b32_e32 v81, 9, v1
	s_mov_b64 s[4:5], -1
	v_lshlrev_b32_e32 v80, 5, v0
	v_lshlrev_b32_e32 v82, 2, v0
	s_cbranch_scc1 .LBB0_831
	s_add_i32 s4, 0, 0x17c00
	s_lshl_b32 s12, s42, 6
	s_lshl_b32 s10, s42, 4
	v_add3_u32 v83, s4, v81, v82
	s_lshl_b64 s[4:5], s[0:1], 21
	v_lshlrev_b32_e32 v0, 4, v148
	v_mov_b32_e32 v8, 0
	s_add_u32 s4, s92, s4
	v_and_b32_e32 v2, 48, v0
	v_lshlrev_b32_e32 v0, 8, v148
	v_mov_b32_e32 v1, v8
	s_addc_u32 s5, s93, s5
	v_lshl_add_u64 v[68:69], s[4:5], 0, v[0:1]
	s_lshl_b64 s[4:5], s[0:1], 23
	v_and_b32_e32 v1, 0x3c00, v0
	v_or_b32_e32 v1, s4, v1
	v_or3_b32 v2, v1, s12, v2
	s_lshl_b64 s[0:1], s[0:1], 24
	v_and_b32_e32 v0, 0x3800, v0
	v_and_b32_e32 v1, 7, v128
	v_mov_b32_e32 v3, s5
	v_or_b32_e32 v0, s0, v0
	s_lshl_b32 s0, s42, 7
	v_lshlrev_b32_e32 v1, 4, v1
	v_readlane_b32 s12, v254, 0
	v_lshl_add_u64 v[2:3], s[92:93], 0, v[2:3]
	s_mov_b64 s[4:5], 0x17b10000
	v_or3_b32 v0, v0, s0, v1
	v_mov_b32_e32 v1, s1
	v_readlane_b32 s18, v254, 6
	v_readlane_b32 s19, v254, 7
	v_mov_b32_e32 v14, v8
	v_mov_b32_e32 v15, v8
	v_lshl_add_u64 v[70:71], v[2:3], 0, s[4:5]
	v_lshl_add_u64 v[72:73], s[92:93], 0, v[0:1]
	v_readlane_b32 s13, v254, 1
	v_readlane_b32 s14, v254, 2
	v_readlane_b32 s15, v254, 3
	v_readlane_b32 s16, v254, 4
	v_readlane_b32 s17, v254, 5
	v_lshl_add_u64 v[74:75], s[18:19], 0, v[0:1]
	v_mov_b32_e32 v0, v8
	v_mov_b32_e32 v1, v8
	v_mov_b32_e32 v2, v8
	v_mov_b32_e32 v3, v8
	v_mov_b32_e32 v4, v8
	v_mov_b32_e32 v5, v8
	v_mov_b32_e32 v6, v8
	v_mov_b32_e32 v7, v8
	v_mov_b32_e32 v9, v8
	v_mov_b32_e32 v10, v8
	v_mov_b32_e32 v11, v8
	v_mov_b32_e32 v12, v8
	v_mov_b32_e32 v13, v8
	v_mov_b64_e32 v[30:31], v[14:15]
	v_mov_b64_e32 v[46:47], v[14:15]
	v_cmp_gt_u32_e64 s[6:7], 32, v148
	s_mov_b32 s33, 4
	v_cmp_gt_u32_e64 s[8:9], 16, v148
	s_mov_b32 s11, 0
	s_mov_b64 s[0:1], 0x2204000
	s_mov_b64 s[12:13], 0
	s_mov_b64 s[14:15], 0x37f20000
	s_mov_b64 s[16:17], 0x37f24000
	s_mov_b64 s[18:19], 0x20000
	s_mov_b64 s[20:21], 0x24000
	s_mov_b64 s[22:23], 0x8020000
	s_mov_b64 s[24:25], 0x8024000
	s_mov_b64 s[26:27], 0xfa20000
	s_mov_b64 s[28:29], 0xfa24000
	s_mov_b64 s[30:31], 0x2000
	s_mov_b64 s[34:35], 0x4000
	v_mov_b64_e32 v[28:29], v[12:13]
	v_mov_b64_e32 v[26:27], v[10:11]
	v_mov_b64_e32 v[24:25], v[8:9]
	v_mov_b64_e32 v[22:23], v[6:7]
	v_mov_b64_e32 v[20:21], v[4:5]
	v_mov_b64_e32 v[18:19], v[2:3]
	v_mov_b64_e32 v[16:17], v[0:1]
	v_mov_b64_e32 v[44:45], v[12:13]
	v_mov_b64_e32 v[42:43], v[10:11]
	v_mov_b64_e32 v[40:41], v[8:9]
	v_mov_b64_e32 v[38:39], v[6:7]
	v_mov_b64_e32 v[36:37], v[4:5]
	v_mov_b64_e32 v[34:35], v[2:3]
	v_mov_b64_e32 v[32:33], v[0:1]
	v_readfirstlane_b32 s64, v72
	v_readfirstlane_b32 s65, v73
	v_readfirstlane_b32 s66, v74
	v_readfirstlane_b32 s67, v75
	v_readfirstlane_b32 s68, v70
	v_readfirstlane_b32 s69, v71
	v_readfirstlane_b32 s70, v68
	v_readfirstlane_b32 s71, v69
	s_nop 1
	v_subrev_u32_e32 v102, s64, v72
	v_subrev_u32_e32 v103, s66, v74
	v_subrev_u32_e32 v104, s68, v70
	v_subrev_u32_e32 v105, s70, v68
	s_branch .LBB0_817

.LBB0_816:
	s_add_u32 s0, s0, 0x1000
	s_addc_u32 s1, s1, 0
	s_waitcnt lgkmcnt(0)
	s_barrier
	s_add_u32 s12, s12, 0x8000
	s_addc_u32 s13, s13, 0
	s_add_i32 s33, s33, 1
	s_add_u32 s68, s68, s34
	s_addc_u32 s69, s69, s35
	s_cmp_eq_u32 s12, 0x1020000
	s_cbranch_scc1 .LBB0_830

.LBB0_826:
	s_mul_i32 s4, s33, 0xcccd
	s_lshr_b32 s4, s4, 18
	s_mul_i32 s4, s4, 5
	s_sub_i32 s4, s33, s4
	s_and_b32 s4, s4, 0xffff
	s_cmp_lg_u32 0, -1
	s_mulk_i32 s4, 0x2900
	s_cselect_b32 s5, 0, 0
	s_add_i32 s4, s5, s4
	s_add_i32 s36, s4, 0x19c00
	s_add_u32 s72, s64, s12
	s_addc_u32 s73, s65, s13
	s_add_u32 s76, s66, s12
	s_addc_u32 s77, s67, s13
	s_add_u32 s74, s72, s14
	s_addc_u32 s75, s73, s15
	s_mov_b32 m0, s36
	s_nop 0
	global_load_lds_dwordx4 v102, s[74:75]
	s_add_i32 s4, s36, 0x400
	s_add_u32 s74, s72, s16
	s_addc_u32 s75, s73, s17
	s_mov_b32 m0, s4
	s_nop 0
	global_load_lds_dwordx4 v102, s[74:75]
	s_add_i32 s4, s36, 0x800
	s_add_u32 s74, s76, s18
	s_addc_u32 s75, s77, s19
	s_mov_b32 m0, s4
	s_nop 0
	global_load_lds_dwordx4 v103, s[74:75]
	s_add_i32 s4, s36, 0xc00
	s_add_u32 s74, s76, s20
	s_addc_u32 s75, s77, s21
	s_mov_b32 m0, s4
	s_nop 0
	global_load_lds_dwordx4 v103, s[74:75]
	s_add_i32 s4, s36, 0x1000
	s_add_u32 s74, s76, s22
	s_addc_u32 s75, s77, s23
	s_mov_b32 m0, s4
	s_nop 0
	global_load_lds_dwordx4 v103, s[74:75]
	s_add_i32 s4, s36, 0x1400
	s_add_u32 s74, s76, s24
	s_addc_u32 s75, s77, s25
	s_mov_b32 m0, s4
	s_nop 0
	global_load_lds_dwordx4 v103, s[74:75]
	s_add_i32 s4, s36, 0x1800
	s_add_u32 s74, s72, s26
	s_addc_u32 s75, s73, s27
	s_mov_b32 m0, s4
	s_nop 0
	global_load_lds_dwordx4 v102, s[74:75]
	s_add_i32 s4, s36, 0x1c00
	s_add_u32 s74, s72, s28
	s_addc_u32 s75, s73, s29
	s_mov_b32 m0, s4
	s_nop 0
	global_load_lds_dwordx4 v102, s[74:75]
	s_and_saveexec_b64 s[4:5], s[6:7]
	s_cbranch_execz .LBB0_828
	s_add_i32 s37, s36, 0x2000
	s_mov_b32 m0, s37
	s_nop 0
	global_load_lds_dwordx4 v104, s[68:69]
	s_add_i32 s37, s36, 0x2200
	s_add_u32 s74, s68, s30
	s_addc_u32 s75, s69, s31
	s_mov_b32 m0, s37
	s_nop 0
	global_load_lds_dwordx4 v104, s[74:75]
.LBB0_828:
	s_or_b64 exec, exec, s[4:5]
	s_and_saveexec_b64 s[4:5], s[8:9]
	s_cbranch_execz .LBB0_815
	s_add_u32 s74, s70, s0
	s_addc_u32 s75, s71, s1
	s_add_u32 s74, s74, s10
	s_addc_u32 s75, s75, s11
	s_addk_i32 s36, 0x2800
	s_mov_b32 m0, s36
	s_nop 0
	global_load_lds_dwordx4 v105, s[74:75]
	s_branch .LBB0_815
